# sweep loops: waves 4-7 start half an iteration later (stagger)
# speedup vs baseline: 1.0088x; 1.0039x over previous
; #define LAS __attribute__((address_space(3)))
;     constexpr int SHIFT = 24 - 8 * (MODE & 3);
;     const int r32 = lane & 31, hi = lane >> 5, ql = 32 * (wid & 1) + r32;
;     LAS unsigned* hist = (LAS unsigned*)(lds + DS_HIST) + ql;   LAS unsigned short* sel = (LAS unsigned short*)(lds + DS_SEL) + ql * 256; LAS unsigned* cnt = (LAS unsigned*)(lds + DS_CNT) + ql;
;     LAS unsigned* cand = (LAS unsigned*)(lds + DS_CAND) + ql * DS_CAP; LAS unsigned* ccnt = (LAS unsigned*)(lds + DS_CCNT) + ql;
;     LAS const unsigned char* iqb = lds + DS_IQ + ql * 528 + hi * 16; LAS const float* wqb = (LAS const float*)(lds + DS_WQ) + ql;
;     const int kt0 = wid >> 1; const int nit = kt0 <= c ? 2 * ((c - kt0) / 4 + 1) : 0;
;     const float t_lo = bucket_lo((int)pref), t_hi = bucket_lo((int)pref + 1);
;     const bf16_t* ikp = Zb + (size_t)(64 * kt0 + r32) * NZ + ZIK + hi * 8;
;     bf16x8 a0, a1;
;     if (nit > 0) { a0 = *(const bf16x8*)ikp; a1 = *(const bf16x8*)(ikp + 16); }
; #pragma unroll 1
;     for (int it = 0; it < nit; ++it) {
;         const int kt = kt0 + 4 * (it >> 1), kb = it & 1;
;         const int itn = it + 1 < nit ? it + 1 : it;
;         const bf16_t* np = ikp + (size_t)(256 * (itn >> 1) + 32 * (itn & 1)) * NZ; const bf16x8 n0 = *(const bf16x8*)np, n1 = *(const bf16x8*)(np + 16);
;         f32x2v sc2[8];
; #pragma unroll
;         for (int r = 0; r < 8; ++r) sc2[r] = (f32x2v){0.f, 0.f};
;     ...
;         { f32x16 zero16;
; #pragma unroll
;           for (int r = 0; r < 16; ++r) zero16[r] = 0.f;
;           f32x16 dA0, dA1, dB0, dB1; float wA0, wA1, wB0, wB1;
;           SW_MF(0, dA0, dA1, wA0, wA1);
;           SW_MF(1, dB0, dB1, wB0, wB1); __builtin_amdgcn_sched_barrier(0);
;           SW_VA(dA0, dA1, wA0, wA1);    __builtin_amdgcn_sched_barrier(0);
;           SW_MF(2, dA0, dA1, wA0, wA1); __builtin_amdgcn_sched_barrier(0);
;           SW_VA(dB0, dB1, wB0, wB1);    __builtin_amdgcn_sched_barrier(0);
;           SW_MF(3, dB0, dB1, wB0, wB1); __builtin_amdgcn_sched_barrier(0);
;           SW_VA(dA0, dA1, wA0, wA1);    __builtin_amdgcn_sched_barrier(0);
;           SW_VA(dB0, dB1, wB0, wB1); }
.LBB0_979:
	v_add_u32_e32 v1, 0x200, v1
	v_cmp_lt_u32_e32 vcc, s62, v1
	ds_write_b32 v0, v155
	s_or_b64 s[0:1], vcc, s[0:1]
	v_add_u32_e32 v0, 0x800, v0
	s_andn2_b64 exec, exec, s[0:1]
	s_cbranch_execnz .LBB0_979
	s_or_b64 exec, exec, s[0:1]
	s_lshr_b32 s24, s3, 7
	v_mov_b32_e32 v0, s24
	v_sub_co_u32_e64 v0, s[18:19], s2, v0
	s_lshl_b32 s0, s69, 5
	v_readfirstlane_b32 s1, v0
	v_lshl_or_b32 v2, s24, 6, v151
	v_mov_b64_e32 v[0:1], s[36:37]
	v_and_or_b32 v169, s0, 32, v151
	s_lshr_b32 s1, s1, 1
	v_mad_u64_u32 v[0:1], s[2:3], v2, s61, v[0:1]
	v_lshlrev_b32_e32 v154, 1, v152
	v_lshlrev_b32_e32 v171, 2, v169
	s_and_b32 s25, s1, 0x7ffffffe
	v_lshl_add_u64 v[0:1], v[0:1], 0, v[154:155]
	s_mov_b64 s[2:3], 0x1300
	v_add_u32_e32 v230, 0x100, v171
	v_mad_u32_u24 v165, v169, s86, v199
	v_add_u32_e32 v167, s51, v171
	s_add_i32 s25, s25, 2
	v_lshl_add_u64 v[140:141], v[0:1], 0, s[2:3]
	s_and_b64 vcc, exec, s[18:19]
	s_waitcnt lgkmcnt(0)
	s_barrier
	s_cbranch_vccnz .LBB0_983
	global_load_dwordx4 v[76:79], v[140:141], off
	global_load_dwordx4 v[72:75], v[140:141], off offset:32
	s_mov_b32 s2, 0
	v_mov_b32_e32 v117, 0x280
	v_mov_b32_e32 v118, 0x2ff
	v_add_u32_e32 v116, 0xfffe0000, v230
	v_mov_b32_e32 v112, 0x2c800000
	v_mov_b32_e32 v113, 0x2c800000
	ds_read2st64_b32 v[80:81], v167 offset1:1
	ds_read2st64_b32 v[82:83], v167 offset0:2 offset1:3
	ds_read2st64_b32 v[84:85], v167 offset0:4 offset1:5
	ds_read2st64_b32 v[86:87], v167 offset0:6 offset1:7
	ds_read_b128 v[0:3], v165
	ds_read_b128 v[4:7], v165 offset:32
	ds_read_b128 v[8:11], v165 offset:64
	ds_read_b128 v[12:15], v165 offset:96
	s_waitcnt lgkmcnt(4)
	v_mov_b32_e32 v104, v81
	v_mov_b32_e32 v106, v83
	v_mov_b32_e32 v108, v85
	v_mov_b32_e32 v110, v87
	s_waitcnt vmcnt(0) lgkmcnt(0)
	s_cmp_lt_u32 s69, 4
	s_cbranch_scc1 .Lstag_m5
	s_sleep 14
.Lstag_m5:
.Lm5_loop:
	v_mfma_f32_32x32x16_bf16 v[16:31], v[76:79], v[0:3], 0
	v_mfma_f32_32x32x16_bf16 v[16:31], v[72:75], v[4:7], v[16:31]
	ds_read_b128 v[0:3], v165 offset:128
	ds_read_b128 v[4:7], v165 offset:160
	v_mfma_f32_32x32x16_bf16 v[32:47], v[76:79], v[8:11], 0
	v_mfma_f32_32x32x16_bf16 v[32:47], v[72:75], v[12:15], v[32:47]
	ds_read_b128 v[8:11], v165 offset:192
	ds_read_b128 v[12:15], v165 offset:224
	s_add_i32 s1, s2, 1
	s_cmp_lt_u32 s1, s25
	s_cselect_b32 s3, s1, s2
	s_lshl_b32 vcc_lo, s3, 7
	s_and_b32 vcc_lo, vcc_lo, 0x7fffff00
	s_lshl_b32 s3, s3, 5
	s_and_b32 s3, s3, 32
	s_or_b32 s3, vcc_lo, s3
	v_mad_u64_u32 v[114:115], vcc, s3, v223, v[140:141]
	global_load_dwordx4 v[64:67], v[114:115], off
	global_load_dwordx4 v[68:71], v[114:115], off offset:32
	v_pk_mul_f32 v[16:17], v[16:17], v[112:113] clamp
	v_pk_mul_f32 v[18:19], v[18:19], v[112:113] clamp
	v_pk_mul_f32 v[20:21], v[20:21], v[112:113] clamp
	v_pk_mul_f32 v[22:23], v[22:23], v[112:113] clamp
	v_pk_mul_f32 v[24:25], v[24:25], v[112:113] clamp
	v_pk_mul_f32 v[26:27], v[26:27], v[112:113] clamp
	v_pk_mul_f32 v[28:29], v[28:29], v[112:113] clamp
	v_pk_mul_f32 v[30:31], v[30:31], v[112:113] clamp
	v_pk_fma_f32 v[88:89], v[16:17], v[80:81], 0 op_sel_hi:[1,0,0]
	v_pk_fma_f32 v[90:91], v[18:19], v[80:81], 0 op_sel_hi:[1,0,0]
	v_pk_fma_f32 v[92:93], v[20:21], v[80:81], 0 op_sel_hi:[1,0,0]
	v_pk_fma_f32 v[94:95], v[22:23], v[80:81], 0 op_sel_hi:[1,0,0]
	v_pk_fma_f32 v[96:97], v[24:25], v[80:81], 0 op_sel_hi:[1,0,0]
	v_pk_fma_f32 v[98:99], v[26:27], v[80:81], 0 op_sel_hi:[1,0,0]
	v_pk_fma_f32 v[100:101], v[28:29], v[80:81], 0 op_sel_hi:[1,0,0]
	v_pk_fma_f32 v[102:103], v[30:31], v[80:81], 0 op_sel_hi:[1,0,0]
	s_waitcnt lgkmcnt(2)
	v_mfma_f32_32x32x16_bf16 v[16:31], v[76:79], v[0:3], 0
	v_mfma_f32_32x32x16_bf16 v[16:31], v[72:75], v[4:7], v[16:31]
	ds_read_b128 v[0:3], v165 offset:256
	ds_read_b128 v[4:7], v165 offset:288
	v_pk_mul_f32 v[32:33], v[32:33], v[112:113] clamp
	v_pk_mul_f32 v[34:35], v[34:35], v[112:113] clamp
	v_pk_mul_f32 v[36:37], v[36:37], v[112:113] clamp
	v_pk_mul_f32 v[38:39], v[38:39], v[112:113] clamp
	v_pk_mul_f32 v[40:41], v[40:41], v[112:113] clamp
	v_pk_mul_f32 v[42:43], v[42:43], v[112:113] clamp
	v_pk_mul_f32 v[44:45], v[44:45], v[112:113] clamp
	v_pk_mul_f32 v[46:47], v[46:47], v[112:113] clamp
	v_pk_fma_f32 v[88:89], v[32:33], v[104:105], v[88:89] op_sel_hi:[1,0,1]
	v_pk_fma_f32 v[90:91], v[34:35], v[104:105], v[90:91] op_sel_hi:[1,0,1]
	v_pk_fma_f32 v[92:93], v[36:37], v[104:105], v[92:93] op_sel_hi:[1,0,1]
	v_pk_fma_f32 v[94:95], v[38:39], v[104:105], v[94:95] op_sel_hi:[1,0,1]
	v_pk_fma_f32 v[96:97], v[40:41], v[104:105], v[96:97] op_sel_hi:[1,0,1]
	v_pk_fma_f32 v[98:99], v[42:43], v[104:105], v[98:99] op_sel_hi:[1,0,1]
	v_pk_fma_f32 v[100:101], v[44:45], v[104:105], v[100:101] op_sel_hi:[1,0,1]
	v_pk_fma_f32 v[102:103], v[46:47], v[104:105], v[102:103] op_sel_hi:[1,0,1]
	s_waitcnt lgkmcnt(2)
	v_mfma_f32_32x32x16_bf16 v[32:47], v[76:79], v[8:11], 0
	v_mfma_f32_32x32x16_bf16 v[32:47], v[72:75], v[12:15], v[32:47]
	ds_read_b128 v[8:11], v165 offset:320
	ds_read_b128 v[12:15], v165 offset:352
	v_pk_mul_f32 v[16:17], v[16:17], v[112:113] clamp
	v_pk_mul_f32 v[18:19], v[18:19], v[112:113] clamp
	v_pk_mul_f32 v[20:21], v[20:21], v[112:113] clamp
	v_pk_mul_f32 v[22:23], v[22:23], v[112:113] clamp
	v_pk_mul_f32 v[24:25], v[24:25], v[112:113] clamp
	v_pk_mul_f32 v[26:27], v[26:27], v[112:113] clamp
	v_pk_mul_f32 v[28:29], v[28:29], v[112:113] clamp
	v_pk_mul_f32 v[30:31], v[30:31], v[112:113] clamp
	v_pk_fma_f32 v[88:89], v[16:17], v[82:83], v[88:89] op_sel_hi:[1,0,1]
	v_pk_fma_f32 v[90:91], v[18:19], v[82:83], v[90:91] op_sel_hi:[1,0,1]
	v_pk_fma_f32 v[92:93], v[20:21], v[82:83], v[92:93] op_sel_hi:[1,0,1]
	v_pk_fma_f32 v[94:95], v[22:23], v[82:83], v[94:95] op_sel_hi:[1,0,1]
	v_pk_fma_f32 v[96:97], v[24:25], v[82:83], v[96:97] op_sel_hi:[1,0,1]
	v_pk_fma_f32 v[98:99], v[26:27], v[82:83], v[98:99] op_sel_hi:[1,0,1]
	v_pk_fma_f32 v[100:101], v[28:29], v[82:83], v[100:101] op_sel_hi:[1,0,1]
	v_pk_fma_f32 v[102:103], v[30:31], v[82:83], v[102:103] op_sel_hi:[1,0,1]
	s_waitcnt lgkmcnt(2)
;     ...
;         { f32x16 zero16;
; #pragma unroll
;           for (int r = 0; r < 16; ++r) zero16[r] = 0.f;
;           f32x16 dA0, dA1, dB0, dB1; float wA0, wA1, wB0, wB1;
;           SW_MF(0, dA0, dA1, wA0, wA1);
;           SW_MF(1, dB0, dB1, wB0, wB1); __builtin_amdgcn_sched_barrier(0);
;           SW_VA(dA0, dA1, wA0, wA1);    __builtin_amdgcn_sched_barrier(0);
;           SW_MF(2, dA0, dA1, wA0, wA1); __builtin_amdgcn_sched_barrier(0);
;           SW_VA(dB0, dB1, wB0, wB1);    __builtin_amdgcn_sched_barrier(0);
;           SW_MF(3, dB0, dB1, wB0, wB1); __builtin_amdgcn_sched_barrier(0);
;           SW_VA(dA0, dA1, wA0, wA1);    __builtin_amdgcn_sched_barrier(0);
;           SW_VA(dB0, dB1, wB0, wB1); }
	v_mfma_f32_32x32x16_bf16 v[16:31], v[76:79], v[0:3], 0
	v_mfma_f32_32x32x16_bf16 v[16:31], v[72:75], v[4:7], v[16:31]
	ds_read_b128 v[0:3], v165 offset:384
	ds_read_b128 v[4:7], v165 offset:416
	v_pk_mul_f32 v[32:33], v[32:33], v[112:113] clamp
	v_pk_mul_f32 v[34:35], v[34:35], v[112:113] clamp
	v_pk_mul_f32 v[36:37], v[36:37], v[112:113] clamp
	v_pk_mul_f32 v[38:39], v[38:39], v[112:113] clamp
	v_pk_mul_f32 v[40:41], v[40:41], v[112:113] clamp
	v_pk_mul_f32 v[42:43], v[42:43], v[112:113] clamp
	v_pk_mul_f32 v[44:45], v[44:45], v[112:113] clamp
	v_pk_mul_f32 v[46:47], v[46:47], v[112:113] clamp
	v_pk_fma_f32 v[88:89], v[32:33], v[106:107], v[88:89] op_sel_hi:[1,0,1]
	v_pk_fma_f32 v[90:91], v[34:35], v[106:107], v[90:91] op_sel_hi:[1,0,1]
	v_pk_fma_f32 v[92:93], v[36:37], v[106:107], v[92:93] op_sel_hi:[1,0,1]
	v_pk_fma_f32 v[94:95], v[38:39], v[106:107], v[94:95] op_sel_hi:[1,0,1]
	v_pk_fma_f32 v[96:97], v[40:41], v[106:107], v[96:97] op_sel_hi:[1,0,1]
	v_pk_fma_f32 v[98:99], v[42:43], v[106:107], v[98:99] op_sel_hi:[1,0,1]
	v_pk_fma_f32 v[100:101], v[44:45], v[106:107], v[100:101] op_sel_hi:[1,0,1]
	v_pk_fma_f32 v[102:103], v[46:47], v[106:107], v[102:103] op_sel_hi:[1,0,1]
	s_waitcnt lgkmcnt(2)
	v_mfma_f32_32x32x16_bf16 v[32:47], v[76:79], v[8:11], 0
	v_mfma_f32_32x32x16_bf16 v[32:47], v[72:75], v[12:15], v[32:47]
	ds_read_b128 v[8:11], v165 offset:448
	ds_read_b128 v[12:15], v165 offset:480
	v_pk_mul_f32 v[16:17], v[16:17], v[112:113] clamp
	v_pk_mul_f32 v[18:19], v[18:19], v[112:113] clamp
	v_pk_mul_f32 v[20:21], v[20:21], v[112:113] clamp
	v_pk_mul_f32 v[22:23], v[22:23], v[112:113] clamp
	v_pk_mul_f32 v[24:25], v[24:25], v[112:113] clamp
	v_pk_mul_f32 v[26:27], v[26:27], v[112:113] clamp
	v_pk_mul_f32 v[28:29], v[28:29], v[112:113] clamp
	v_pk_mul_f32 v[30:31], v[30:31], v[112:113] clamp
	v_pk_fma_f32 v[88:89], v[16:17], v[84:85], v[88:89] op_sel_hi:[1,0,1]
	v_pk_fma_f32 v[90:91], v[18:19], v[84:85], v[90:91] op_sel_hi:[1,0,1]
	v_pk_fma_f32 v[92:93], v[20:21], v[84:85], v[92:93] op_sel_hi:[1,0,1]
	v_pk_fma_f32 v[94:95], v[22:23], v[84:85], v[94:95] op_sel_hi:[1,0,1]
	v_pk_fma_f32 v[96:97], v[24:25], v[84:85], v[96:97] op_sel_hi:[1,0,1]
	v_pk_fma_f32 v[98:99], v[26:27], v[84:85], v[98:99] op_sel_hi:[1,0,1]
	v_pk_fma_f32 v[100:101], v[28:29], v[84:85], v[100:101] op_sel_hi:[1,0,1]
	v_pk_fma_f32 v[102:103], v[30:31], v[84:85], v[102:103] op_sel_hi:[1,0,1]
	s_waitcnt lgkmcnt(2)
	v_mfma_f32_32x32x16_bf16 v[16:31], v[76:79], v[0:3], 0
	v_mfma_f32_32x32x16_bf16 v[16:31], v[72:75], v[4:7], v[16:31]
	ds_read_b128 v[0:3], v165
	ds_read_b128 v[4:7], v165 offset:32
	v_pk_mul_f32 v[32:33], v[32:33], v[112:113] clamp
	v_pk_mul_f32 v[34:35], v[34:35], v[112:113] clamp
	v_pk_mul_f32 v[36:37], v[36:37], v[112:113] clamp
	v_pk_mul_f32 v[38:39], v[38:39], v[112:113] clamp
	v_pk_mul_f32 v[40:41], v[40:41], v[112:113] clamp
	v_pk_mul_f32 v[42:43], v[42:43], v[112:113] clamp
	v_pk_mul_f32 v[44:45], v[44:45], v[112:113] clamp
	v_pk_mul_f32 v[46:47], v[46:47], v[112:113] clamp
	v_pk_fma_f32 v[88:89], v[32:33], v[108:109], v[88:89] op_sel_hi:[1,0,1]
	v_pk_fma_f32 v[90:91], v[34:35], v[108:109], v[90:91] op_sel_hi:[1,0,1]
	v_pk_fma_f32 v[92:93], v[36:37], v[108:109], v[92:93] op_sel_hi:[1,0,1]
	v_pk_fma_f32 v[94:95], v[38:39], v[108:109], v[94:95] op_sel_hi:[1,0,1]
	v_pk_fma_f32 v[96:97], v[40:41], v[108:109], v[96:97] op_sel_hi:[1,0,1]
	v_pk_fma_f32 v[98:99], v[42:43], v[108:109], v[98:99] op_sel_hi:[1,0,1]
	v_pk_fma_f32 v[100:101], v[44:45], v[108:109], v[100:101] op_sel_hi:[1,0,1]
	v_pk_fma_f32 v[102:103], v[46:47], v[108:109], v[102:103] op_sel_hi:[1,0,1]
	s_waitcnt lgkmcnt(2)
; __device__ __forceinline__ int bucketf(float f) { const unsigned u = __float_as_uint(f); const int idx = (int)((u >> 20) & 0x7FFu); const int c = min(max(idx - 816, 128), 255); return c ^ (((int)u >> 31) & 255); }
;     ...
;         { f32x16 zero16;
; #pragma unroll
;           for (int r = 0; r < 16; ++r) zero16[r] = 0.f;
;           f32x16 dA0, dA1, dB0, dB1; float wA0, wA1, wB0, wB1;
;           SW_MF(0, dA0, dA1, wA0, wA1);
;           SW_MF(1, dB0, dB1, wB0, wB1); __builtin_amdgcn_sched_barrier(0);
;           SW_VA(dA0, dA1, wA0, wA1);    __builtin_amdgcn_sched_barrier(0);
;           SW_MF(2, dA0, dA1, wA0, wA1); __builtin_amdgcn_sched_barrier(0);
;           SW_VA(dB0, dB1, wB0, wB1);    __builtin_amdgcn_sched_barrier(0);
;           SW_MF(3, dB0, dB1, wB0, wB1); __builtin_amdgcn_sched_barrier(0);
;           SW_VA(dA0, dA1, wA0, wA1);    __builtin_amdgcn_sched_barrier(0);
;           SW_VA(dB0, dB1, wB0, wB1); }
;     ...
;         f32x16 sc;
; #pragma unroll
;         for (int r = 0; r < 16; ++r) sc[r] = sc2[r >> 1][r & 1];
;         const unsigned s0 = (unsigned)(64 * kt + 32 * kb + 4 * hi);
; #pragma unroll
;         for (int r = 0; r < 16; ++r) { const unsigned s = s0 + (unsigned)((r & 3) + 8 * (r >> 2));
;             if (MODE == 5) { __hip_atomic_fetch_add(hist + 64 * bucketf(sc[r]), 1u, __ATOMIC_RELAXED, __HIP_MEMORY_SCOPE_WORKGROUP); continue; }
	v_mfma_f32_32x32x16_bf16 v[32:47], v[76:79], v[8:11], 0
	v_mfma_f32_32x32x16_bf16 v[32:47], v[72:75], v[12:15], v[32:47]
	ds_read_b128 v[8:11], v165 offset:64
	ds_read_b128 v[12:15], v165 offset:96
	v_pk_mul_f32 v[16:17], v[16:17], v[112:113] clamp
	v_pk_mul_f32 v[18:19], v[18:19], v[112:113] clamp
	v_pk_mul_f32 v[20:21], v[20:21], v[112:113] clamp
	v_pk_mul_f32 v[22:23], v[22:23], v[112:113] clamp
	v_pk_mul_f32 v[24:25], v[24:25], v[112:113] clamp
	v_pk_mul_f32 v[26:27], v[26:27], v[112:113] clamp
	v_pk_mul_f32 v[28:29], v[28:29], v[112:113] clamp
	v_pk_mul_f32 v[30:31], v[30:31], v[112:113] clamp
	v_pk_fma_f32 v[88:89], v[16:17], v[86:87], v[88:89] op_sel_hi:[1,0,1]
	v_pk_fma_f32 v[90:91], v[18:19], v[86:87], v[90:91] op_sel_hi:[1,0,1]
	v_pk_fma_f32 v[92:93], v[20:21], v[86:87], v[92:93] op_sel_hi:[1,0,1]
	v_pk_fma_f32 v[94:95], v[22:23], v[86:87], v[94:95] op_sel_hi:[1,0,1]
	v_pk_fma_f32 v[96:97], v[24:25], v[86:87], v[96:97] op_sel_hi:[1,0,1]
	v_pk_fma_f32 v[98:99], v[26:27], v[86:87], v[98:99] op_sel_hi:[1,0,1]
	v_pk_fma_f32 v[100:101], v[28:29], v[86:87], v[100:101] op_sel_hi:[1,0,1]
	v_pk_fma_f32 v[102:103], v[30:31], v[86:87], v[102:103] op_sel_hi:[1,0,1]
	v_pk_mul_f32 v[32:33], v[32:33], v[112:113] clamp
	v_pk_mul_f32 v[34:35], v[34:35], v[112:113] clamp
	v_pk_mul_f32 v[36:37], v[36:37], v[112:113] clamp
	v_pk_mul_f32 v[38:39], v[38:39], v[112:113] clamp
	v_pk_mul_f32 v[40:41], v[40:41], v[112:113] clamp
	v_pk_mul_f32 v[42:43], v[42:43], v[112:113] clamp
	v_pk_mul_f32 v[44:45], v[44:45], v[112:113] clamp
	v_pk_mul_f32 v[46:47], v[46:47], v[112:113] clamp
	v_pk_fma_f32 v[88:89], v[32:33], v[110:111], v[88:89] op_sel_hi:[1,0,1]
	v_pk_fma_f32 v[90:91], v[34:35], v[110:111], v[90:91] op_sel_hi:[1,0,1]
	v_pk_fma_f32 v[92:93], v[36:37], v[110:111], v[92:93] op_sel_hi:[1,0,1]
	v_pk_fma_f32 v[94:95], v[38:39], v[110:111], v[94:95] op_sel_hi:[1,0,1]
	v_pk_fma_f32 v[96:97], v[40:41], v[110:111], v[96:97] op_sel_hi:[1,0,1]
	v_pk_fma_f32 v[98:99], v[42:43], v[110:111], v[98:99] op_sel_hi:[1,0,1]
	v_pk_fma_f32 v[100:101], v[44:45], v[110:111], v[100:101] op_sel_hi:[1,0,1]
	v_pk_fma_f32 v[102:103], v[46:47], v[110:111], v[102:103] op_sel_hi:[1,0,1]
	s_waitcnt lgkmcnt(0)
	v_bfe_u32 v48, v88, 20, 11
	v_ashrrev_i32_e32 v49, 31, v88
	v_med3_u32 v48, v48, v117, v118
	v_bitop3_b32 v48, v48, v49, s56 bitop3:0x78
	v_lshl_add_u32 v48, v48, 8, v116
	ds_add_u32 v48, v222
	v_bfe_u32 v50, v89, 20, 11
	v_ashrrev_i32_e32 v51, 31, v89
	v_med3_u32 v50, v50, v117, v118
	v_bitop3_b32 v50, v50, v51, s56 bitop3:0x78
	v_lshl_add_u32 v50, v50, 8, v116
	ds_add_u32 v50, v222
	v_bfe_u32 v52, v90, 20, 11
	v_ashrrev_i32_e32 v53, 31, v90
	v_med3_u32 v52, v52, v117, v118
	v_bitop3_b32 v52, v52, v53, s56 bitop3:0x78
	v_lshl_add_u32 v52, v52, 8, v116
	ds_add_u32 v52, v222
	v_bfe_u32 v54, v91, 20, 11
	v_ashrrev_i32_e32 v55, 31, v91
	v_med3_u32 v54, v54, v117, v118
	v_bitop3_b32 v54, v54, v55, s56 bitop3:0x78
	v_lshl_add_u32 v54, v54, 8, v116
	ds_add_u32 v54, v222
	v_bfe_u32 v48, v92, 20, 11
	v_ashrrev_i32_e32 v49, 31, v92
	v_med3_u32 v48, v48, v117, v118
	v_bitop3_b32 v48, v48, v49, s56 bitop3:0x78
	v_lshl_add_u32 v48, v48, 8, v116
	ds_add_u32 v48, v222
	v_bfe_u32 v50, v93, 20, 11
	v_ashrrev_i32_e32 v51, 31, v93
	v_med3_u32 v50, v50, v117, v118
	v_bitop3_b32 v50, v50, v51, s56 bitop3:0x78
	v_lshl_add_u32 v50, v50, 8, v116
	ds_add_u32 v50, v222
	v_bfe_u32 v52, v94, 20, 11
	v_ashrrev_i32_e32 v53, 31, v94
	v_med3_u32 v52, v52, v117, v118
	v_bitop3_b32 v52, v52, v53, s56 bitop3:0x78
	v_lshl_add_u32 v52, v52, 8, v116
	ds_add_u32 v52, v222
	v_bfe_u32 v54, v95, 20, 11
	v_ashrrev_i32_e32 v55, 31, v95
	v_med3_u32 v54, v54, v117, v118
	v_bitop3_b32 v54, v54, v55, s56 bitop3:0x78
	v_lshl_add_u32 v54, v54, 8, v116
	ds_add_u32 v54, v222
	v_bfe_u32 v48, v96, 20, 11
	v_ashrrev_i32_e32 v49, 31, v96
	v_med3_u32 v48, v48, v117, v118
	v_bitop3_b32 v48, v48, v49, s56 bitop3:0x78
	v_lshl_add_u32 v48, v48, 8, v116
	ds_add_u32 v48, v222
	v_bfe_u32 v50, v97, 20, 11
	v_ashrrev_i32_e32 v51, 31, v97
	v_med3_u32 v50, v50, v117, v118
	v_bitop3_b32 v50, v50, v51, s56 bitop3:0x78
	v_lshl_add_u32 v50, v50, 8, v116
	ds_add_u32 v50, v222
	v_bfe_u32 v52, v98, 20, 11
	v_ashrrev_i32_e32 v53, 31, v98
	v_med3_u32 v52, v52, v117, v118
	v_bitop3_b32 v52, v52, v53, s56 bitop3:0x78
	v_lshl_add_u32 v52, v52, 8, v116
	ds_add_u32 v52, v222
	v_bfe_u32 v54, v99, 20, 11
	v_ashrrev_i32_e32 v55, 31, v99
	v_med3_u32 v54, v54, v117, v118
	v_bitop3_b32 v54, v54, v55, s56 bitop3:0x78
	v_lshl_add_u32 v54, v54, 8, v116
	ds_add_u32 v54, v222
	v_bfe_u32 v48, v100, 20, 11
	v_ashrrev_i32_e32 v49, 31, v100
	v_med3_u32 v48, v48, v117, v118
	v_bitop3_b32 v48, v48, v49, s56 bitop3:0x78
	v_lshl_add_u32 v48, v48, 8, v116
	ds_add_u32 v48, v222
	v_bfe_u32 v50, v101, 20, 11
	v_ashrrev_i32_e32 v51, 31, v101
	v_med3_u32 v50, v50, v117, v118
	v_bitop3_b32 v50, v50, v51, s56 bitop3:0x78
	v_lshl_add_u32 v50, v50, 8, v116
	ds_add_u32 v50, v222
	v_bfe_u32 v52, v102, 20, 11
	v_ashrrev_i32_e32 v53, 31, v102
	v_med3_u32 v52, v52, v117, v118
	v_bitop3_b32 v52, v52, v53, s56 bitop3:0x78
	v_lshl_add_u32 v52, v52, 8, v116
	ds_add_u32 v52, v222
	v_bfe_u32 v54, v103, 20, 11
	v_ashrrev_i32_e32 v55, 31, v103
	v_med3_u32 v54, v54, v117, v118
	v_bitop3_b32 v54, v54, v55, s56 bitop3:0x78
	v_lshl_add_u32 v54, v54, 8, v116
	ds_add_u32 v54, v222
	s_waitcnt vmcnt(0)
	v_mov_b64_e32 v[76:77], v[64:65]
	v_mov_b64_e32 v[78:79], v[66:67]
	v_mov_b64_e32 v[72:73], v[68:69]
	v_mov_b64_e32 v[74:75], v[70:71]
	s_cmp_lg_u32 s25, s1
	s_mov_b32 s2, s1
	s_cbranch_scc1 .Lm5_loop

; #define LAS __attribute__((address_space(3)))
;     constexpr int SHIFT = 24 - 8 * (MODE & 3);
;     const int r32 = lane & 31, hi = lane >> 5, ql = 32 * (wid & 1) + r32;
;     LAS unsigned* hist = (LAS unsigned*)(lds + DS_HIST) + ql;   LAS unsigned short* sel = (LAS unsigned short*)(lds + DS_SEL) + ql * 256; LAS unsigned* cnt = (LAS unsigned*)(lds + DS_CNT) + ql;
;     LAS unsigned* cand = (LAS unsigned*)(lds + DS_CAND) + ql * DS_CAP; LAS unsigned* ccnt = (LAS unsigned*)(lds + DS_CCNT) + ql;
;     LAS const unsigned char* iqb = lds + DS_IQ + ql * 528 + hi * 16; LAS const float* wqb = (LAS const float*)(lds + DS_WQ) + ql;
;     const int kt0 = wid >> 1; const int nit = kt0 <= c ? 2 * ((c - kt0) / 4 + 1) : 0;
;     const float t_lo = bucket_lo((int)pref), t_hi = bucket_lo((int)pref + 1);
;     const bf16_t* ikp = Zb + (size_t)(64 * kt0 + r32) * NZ + ZIK + hi * 8;
;     bf16x8 a0, a1;
;     if (nit > 0) { a0 = *(const bf16x8*)ikp; a1 = *(const bf16x8*)(ikp + 16); }
; #pragma unroll 1
;     for (int it = 0; it < nit; ++it) {
;         const int kt = kt0 + 4 * (it >> 1), kb = it & 1;
;         const int itn = it + 1 < nit ? it + 1 : it;
;         const bf16_t* np = ikp + (size_t)(256 * (itn >> 1) + 32 * (itn & 1)) * NZ; const bf16x8 n0 = *(const bf16x8*)np, n1 = *(const bf16x8*)(np + 16);
;         f32x2v sc2[8];
; #pragma unroll
;         for (int r = 0; r < 8; ++r) sc2[r] = (f32x2v){0.f, 0.f};
;     ...
;         { f32x16 zero16;
; #pragma unroll
;           for (int r = 0; r < 16; ++r) zero16[r] = 0.f;
;           f32x16 dA0, dA1, dB0, dB1; float wA0, wA1, wB0, wB1;
;           SW_MF(0, dA0, dA1, wA0, wA1);
;           SW_MF(1, dB0, dB1, wB0, wB1); __builtin_amdgcn_sched_barrier(0);
;           SW_VA(dA0, dA1, wA0, wA1);    __builtin_amdgcn_sched_barrier(0);
;           SW_MF(2, dA0, dA1, wA0, wA1); __builtin_amdgcn_sched_barrier(0);
;           SW_VA(dB0, dB1, wB0, wB1);    __builtin_amdgcn_sched_barrier(0);
;           SW_MF(3, dB0, dB1, wB0, wB1); __builtin_amdgcn_sched_barrier(0);
;           SW_VA(dA0, dA1, wA0, wA1);    __builtin_amdgcn_sched_barrier(0);
;           SW_VA(dB0, dB1, wB0, wB1); }
.LBB0_1521:
	s_and_b64 vcc, exec, s[18:19]
	s_cbranch_vccnz .LBB0_1620
	v_lshl_add_u32 v179, v169, 9, s57
	v_add_u32_e32 v180, s94, v171
	v_lshl_add_u32 v169, v169, 10, v200
	v_add_u32_e32 v171, s33, v171
	v_mul_f32_e32 v122, 0x2c800000, v154
	v_mul_f32_e32 v123, 0x2c800000, v178
	s_mov_b32 s18, 0
	v_mov_b32_e32 v112, 0x2c800000
	v_mov_b32_e32 v113, 0x2c800000
	ds_read2st64_b32 v[80:81], v167 offset1:1
	ds_read2st64_b32 v[82:83], v167 offset0:2 offset1:3
	ds_read2st64_b32 v[84:85], v167 offset0:4 offset1:5
	ds_read2st64_b32 v[86:87], v167 offset0:6 offset1:7
	ds_read_b128 v[0:3], v165
	ds_read_b128 v[4:7], v165 offset:32
	ds_read_b128 v[8:11], v165 offset:64
	ds_read_b128 v[12:15], v165 offset:96
	s_waitcnt lgkmcnt(4)
	v_mov_b32_e32 v104, v81
	v_mov_b32_e32 v106, v83
	v_mov_b32_e32 v108, v85
	v_mov_b32_e32 v110, v87
	s_waitcnt vmcnt(0) lgkmcnt(0)
	s_cmp_lt_u32 s69, 4
	s_cbranch_scc1 .Lstag_m6
	s_sleep 14
.Lstag_m6:
.Lm6_loop:
	v_mfma_f32_32x32x16_bf16 v[16:31], v[132:135], v[0:3], 0
	v_mfma_f32_32x32x16_bf16 v[16:31], v[128:131], v[4:7], v[16:31]
	ds_read_b128 v[0:3], v165 offset:128
	ds_read_b128 v[4:7], v165 offset:160
	v_mfma_f32_32x32x16_bf16 v[32:47], v[132:135], v[8:11], 0
	v_mfma_f32_32x32x16_bf16 v[32:47], v[128:131], v[12:15], v[32:47]
	ds_read_b128 v[8:11], v165 offset:192
	ds_read_b128 v[12:15], v165 offset:224
	s_add_i32 s1, s18, 1
	s_cmp_lt_u32 s1, s25
	s_cselect_b32 s3, s1, s18
	s_lshl_b32 vcc_lo, s3, 7
	s_and_b32 vcc_lo, vcc_lo, 0x7fffff00
	s_lshl_b32 s3, s3, 5
	s_and_b32 s3, s3, 32
	s_or_b32 s3, vcc_lo, s3
	v_mad_u64_u32 v[114:115], vcc, s3, v223, v[140:141]
	s_lshr_b32 s0, s18, 1
	s_lshl_b32 s0, s0, 2
	s_add_i32 s0, s0, s24
	s_lshl_b32 s0, s0, 6
	s_and_b32 s2, s18, 1
	s_lshl_b32 s2, s2, 5
	s_or_b32 s0, s0, s2
	v_or_b32_e32 v124, s0, v159
	global_load_dwordx4 v[64:67], v[114:115], off
	global_load_dwordx4 v[68:71], v[114:115], off offset:32
	v_pk_mul_f32 v[16:17], v[16:17], v[112:113] clamp
	v_pk_mul_f32 v[18:19], v[18:19], v[112:113] clamp
	v_pk_mul_f32 v[20:21], v[20:21], v[112:113] clamp
	v_pk_mul_f32 v[22:23], v[22:23], v[112:113] clamp
	v_pk_mul_f32 v[24:25], v[24:25], v[112:113] clamp
	v_pk_mul_f32 v[26:27], v[26:27], v[112:113] clamp
	v_pk_mul_f32 v[28:29], v[28:29], v[112:113] clamp
	v_pk_mul_f32 v[30:31], v[30:31], v[112:113] clamp
	v_pk_fma_f32 v[88:89], v[16:17], v[80:81], 0 op_sel_hi:[1,0,0]
	v_pk_fma_f32 v[90:91], v[18:19], v[80:81], 0 op_sel_hi:[1,0,0]
	v_pk_fma_f32 v[92:93], v[20:21], v[80:81], 0 op_sel_hi:[1,0,0]
	v_pk_fma_f32 v[94:95], v[22:23], v[80:81], 0 op_sel_hi:[1,0,0]
	v_pk_fma_f32 v[96:97], v[24:25], v[80:81], 0 op_sel_hi:[1,0,0]
	v_pk_fma_f32 v[98:99], v[26:27], v[80:81], 0 op_sel_hi:[1,0,0]
	v_pk_fma_f32 v[100:101], v[28:29], v[80:81], 0 op_sel_hi:[1,0,0]
	v_pk_fma_f32 v[102:103], v[30:31], v[80:81], 0 op_sel_hi:[1,0,0]
	s_waitcnt lgkmcnt(2)
	v_mfma_f32_32x32x16_bf16 v[16:31], v[132:135], v[0:3], 0
	v_mfma_f32_32x32x16_bf16 v[16:31], v[128:131], v[4:7], v[16:31]
	ds_read_b128 v[0:3], v165 offset:256
	ds_read_b128 v[4:7], v165 offset:288
	v_pk_mul_f32 v[32:33], v[32:33], v[112:113] clamp
	v_pk_mul_f32 v[34:35], v[34:35], v[112:113] clamp
	v_pk_mul_f32 v[36:37], v[36:37], v[112:113] clamp
	v_pk_mul_f32 v[38:39], v[38:39], v[112:113] clamp
	v_pk_mul_f32 v[40:41], v[40:41], v[112:113] clamp
	v_pk_mul_f32 v[42:43], v[42:43], v[112:113] clamp
	v_pk_mul_f32 v[44:45], v[44:45], v[112:113] clamp
	v_pk_mul_f32 v[46:47], v[46:47], v[112:113] clamp
	v_pk_fma_f32 v[88:89], v[32:33], v[104:105], v[88:89] op_sel_hi:[1,0,1]
	v_pk_fma_f32 v[90:91], v[34:35], v[104:105], v[90:91] op_sel_hi:[1,0,1]
	v_pk_fma_f32 v[92:93], v[36:37], v[104:105], v[92:93] op_sel_hi:[1,0,1]
	v_pk_fma_f32 v[94:95], v[38:39], v[104:105], v[94:95] op_sel_hi:[1,0,1]
	v_pk_fma_f32 v[96:97], v[40:41], v[104:105], v[96:97] op_sel_hi:[1,0,1]
	v_pk_fma_f32 v[98:99], v[42:43], v[104:105], v[98:99] op_sel_hi:[1,0,1]
	v_pk_fma_f32 v[100:101], v[44:45], v[104:105], v[100:101] op_sel_hi:[1,0,1]
	v_pk_fma_f32 v[102:103], v[46:47], v[104:105], v[102:103] op_sel_hi:[1,0,1]
	s_waitcnt lgkmcnt(2)
	v_mfma_f32_32x32x16_bf16 v[32:47], v[132:135], v[8:11], 0
	v_mfma_f32_32x32x16_bf16 v[32:47], v[128:131], v[12:15], v[32:47]
	ds_read_b128 v[8:11], v165 offset:320
	ds_read_b128 v[12:15], v165 offset:352
	v_pk_mul_f32 v[16:17], v[16:17], v[112:113] clamp
	v_pk_mul_f32 v[18:19], v[18:19], v[112:113] clamp
	v_pk_mul_f32 v[20:21], v[20:21], v[112:113] clamp
	v_pk_mul_f32 v[22:23], v[22:23], v[112:113] clamp
	v_pk_mul_f32 v[24:25], v[24:25], v[112:113] clamp
	v_pk_mul_f32 v[26:27], v[26:27], v[112:113] clamp
	v_pk_mul_f32 v[28:29], v[28:29], v[112:113] clamp
	v_pk_mul_f32 v[30:31], v[30:31], v[112:113] clamp
	v_pk_fma_f32 v[88:89], v[16:17], v[82:83], v[88:89] op_sel_hi:[1,0,1]
	v_pk_fma_f32 v[90:91], v[18:19], v[82:83], v[90:91] op_sel_hi:[1,0,1]
	v_pk_fma_f32 v[92:93], v[20:21], v[82:83], v[92:93] op_sel_hi:[1,0,1]
	v_pk_fma_f32 v[94:95], v[22:23], v[82:83], v[94:95] op_sel_hi:[1,0,1]
	v_pk_fma_f32 v[96:97], v[24:25], v[82:83], v[96:97] op_sel_hi:[1,0,1]
	v_pk_fma_f32 v[98:99], v[26:27], v[82:83], v[98:99] op_sel_hi:[1,0,1]
	v_pk_fma_f32 v[100:101], v[28:29], v[82:83], v[100:101] op_sel_hi:[1,0,1]
	v_pk_fma_f32 v[102:103], v[30:31], v[82:83], v[102:103] op_sel_hi:[1,0,1]
	s_waitcnt lgkmcnt(2)
; __device__ __forceinline__ unsigned sortable(float f) { const unsigned u = __float_as_uint(f); return u ^ ((unsigned)((int)u >> 31) | 0x80000000u); }
; __device__ __forceinline__ int bucketf(float f) { const unsigned u = __float_as_uint(f); const int idx = (int)((u >> 20) & 0x7FFu); const int c = min(max(idx - 816, 128), 255); return c ^ (((int)u >> 31) & 255); }
;     ...
;         { f32x16 zero16;
; #pragma unroll
;           for (int r = 0; r < 16; ++r) zero16[r] = 0.f;
;           f32x16 dA0, dA1, dB0, dB1; float wA0, wA1, wB0, wB1;
;           SW_MF(0, dA0, dA1, wA0, wA1);
;           SW_MF(1, dB0, dB1, wB0, wB1); __builtin_amdgcn_sched_barrier(0);
;           SW_VA(dA0, dA1, wA0, wA1);    __builtin_amdgcn_sched_barrier(0);
;           SW_MF(2, dA0, dA1, wA0, wA1); __builtin_amdgcn_sched_barrier(0);
;           SW_VA(dB0, dB1, wB0, wB1);    __builtin_amdgcn_sched_barrier(0);
;           SW_MF(3, dB0, dB1, wB0, wB1); __builtin_amdgcn_sched_barrier(0);
;           SW_VA(dA0, dA1, wA0, wA1);    __builtin_amdgcn_sched_barrier(0);
;           SW_VA(dB0, dB1, wB0, wB1); }
;     ...
;         f32x16 sc;
; #pragma unroll
;         for (int r = 0; r < 16; ++r) sc[r] = sc2[r >> 1][r & 1];
;         const unsigned s0 = (unsigned)(64 * kt + 32 * kb + 4 * hi);
; #pragma unroll
;         for (int r = 0; r < 16; ++r) { const unsigned s = s0 + (unsigned)((r & 3) + 8 * (r >> 2));
;             if (MODE == 5) { __hip_atomic_fetch_add(hist + 64 * bucketf(sc[r]), 1u, __ATOMIC_RELAXED, __HIP_MEMORY_SCOPE_WORKGROUP); continue; }
;             if (MODE == 6) {
;                 if (sc[r] >= t_hi) { const unsigned pos = __hip_atomic_fetch_add(cnt, 1u, __ATOMIC_RELAXED, __HIP_MEMORY_SCOPE_WORKGROUP); sel[pos & 255u] = (unsigned short)s; }
;                 else if (sc[r] >= t_lo) { const unsigned key = (sortable(sc[r]) & 0xFFFFE000u) | (8191u - s);
;                     const unsigned pos = __hip_atomic_fetch_add(ccnt, 1u, __ATOMIC_RELAXED, __HIP_MEMORY_SCOPE_WORKGROUP); cand[pos & (DS_CAP - 1)] = key; }
	v_mfma_f32_32x32x16_bf16 v[16:31], v[132:135], v[0:3], 0
	v_mfma_f32_32x32x16_bf16 v[16:31], v[128:131], v[4:7], v[16:31]
	ds_read_b128 v[0:3], v165 offset:384
	ds_read_b128 v[4:7], v165 offset:416
	v_pk_mul_f32 v[32:33], v[32:33], v[112:113] clamp
	v_pk_mul_f32 v[34:35], v[34:35], v[112:113] clamp
	v_pk_mul_f32 v[36:37], v[36:37], v[112:113] clamp
	v_pk_mul_f32 v[38:39], v[38:39], v[112:113] clamp
	v_pk_mul_f32 v[40:41], v[40:41], v[112:113] clamp
	v_pk_mul_f32 v[42:43], v[42:43], v[112:113] clamp
	v_pk_mul_f32 v[44:45], v[44:45], v[112:113] clamp
	v_pk_mul_f32 v[46:47], v[46:47], v[112:113] clamp
	v_pk_fma_f32 v[88:89], v[32:33], v[106:107], v[88:89] op_sel_hi:[1,0,1]
	v_pk_fma_f32 v[90:91], v[34:35], v[106:107], v[90:91] op_sel_hi:[1,0,1]
	v_pk_fma_f32 v[92:93], v[36:37], v[106:107], v[92:93] op_sel_hi:[1,0,1]
	v_pk_fma_f32 v[94:95], v[38:39], v[106:107], v[94:95] op_sel_hi:[1,0,1]
	v_pk_fma_f32 v[96:97], v[40:41], v[106:107], v[96:97] op_sel_hi:[1,0,1]
	v_pk_fma_f32 v[98:99], v[42:43], v[106:107], v[98:99] op_sel_hi:[1,0,1]
	v_pk_fma_f32 v[100:101], v[44:45], v[106:107], v[100:101] op_sel_hi:[1,0,1]
	v_pk_fma_f32 v[102:103], v[46:47], v[106:107], v[102:103] op_sel_hi:[1,0,1]
	s_waitcnt lgkmcnt(2)
	v_mfma_f32_32x32x16_bf16 v[32:47], v[132:135], v[8:11], 0
	v_mfma_f32_32x32x16_bf16 v[32:47], v[128:131], v[12:15], v[32:47]
	ds_read_b128 v[8:11], v165 offset:448
	ds_read_b128 v[12:15], v165 offset:480
	v_pk_mul_f32 v[16:17], v[16:17], v[112:113] clamp
	v_pk_mul_f32 v[18:19], v[18:19], v[112:113] clamp
	v_pk_mul_f32 v[20:21], v[20:21], v[112:113] clamp
	v_pk_mul_f32 v[22:23], v[22:23], v[112:113] clamp
	v_pk_mul_f32 v[24:25], v[24:25], v[112:113] clamp
	v_pk_mul_f32 v[26:27], v[26:27], v[112:113] clamp
	v_pk_mul_f32 v[28:29], v[28:29], v[112:113] clamp
	v_pk_mul_f32 v[30:31], v[30:31], v[112:113] clamp
	v_pk_fma_f32 v[88:89], v[16:17], v[84:85], v[88:89] op_sel_hi:[1,0,1]
	v_pk_fma_f32 v[90:91], v[18:19], v[84:85], v[90:91] op_sel_hi:[1,0,1]
	v_pk_fma_f32 v[92:93], v[20:21], v[84:85], v[92:93] op_sel_hi:[1,0,1]
	v_pk_fma_f32 v[94:95], v[22:23], v[84:85], v[94:95] op_sel_hi:[1,0,1]
	v_pk_fma_f32 v[96:97], v[24:25], v[84:85], v[96:97] op_sel_hi:[1,0,1]
	v_pk_fma_f32 v[98:99], v[26:27], v[84:85], v[98:99] op_sel_hi:[1,0,1]
	v_pk_fma_f32 v[100:101], v[28:29], v[84:85], v[100:101] op_sel_hi:[1,0,1]
	v_pk_fma_f32 v[102:103], v[30:31], v[84:85], v[102:103] op_sel_hi:[1,0,1]
	s_waitcnt lgkmcnt(2)
	v_mfma_f32_32x32x16_bf16 v[16:31], v[132:135], v[0:3], 0
	v_mfma_f32_32x32x16_bf16 v[16:31], v[128:131], v[4:7], v[16:31]
	ds_read_b128 v[0:3], v165
	ds_read_b128 v[4:7], v165 offset:32
	v_pk_mul_f32 v[32:33], v[32:33], v[112:113] clamp
	v_pk_mul_f32 v[34:35], v[34:35], v[112:113] clamp
	v_pk_mul_f32 v[36:37], v[36:37], v[112:113] clamp
	v_pk_mul_f32 v[38:39], v[38:39], v[112:113] clamp
	v_pk_mul_f32 v[40:41], v[40:41], v[112:113] clamp
	v_pk_mul_f32 v[42:43], v[42:43], v[112:113] clamp
	v_pk_mul_f32 v[44:45], v[44:45], v[112:113] clamp
	v_pk_mul_f32 v[46:47], v[46:47], v[112:113] clamp
	v_pk_fma_f32 v[88:89], v[32:33], v[108:109], v[88:89] op_sel_hi:[1,0,1]
	v_pk_fma_f32 v[90:91], v[34:35], v[108:109], v[90:91] op_sel_hi:[1,0,1]
	v_pk_fma_f32 v[92:93], v[36:37], v[108:109], v[92:93] op_sel_hi:[1,0,1]
	v_pk_fma_f32 v[94:95], v[38:39], v[108:109], v[94:95] op_sel_hi:[1,0,1]
	v_pk_fma_f32 v[96:97], v[40:41], v[108:109], v[96:97] op_sel_hi:[1,0,1]
	v_pk_fma_f32 v[98:99], v[42:43], v[108:109], v[98:99] op_sel_hi:[1,0,1]
	v_pk_fma_f32 v[100:101], v[44:45], v[108:109], v[100:101] op_sel_hi:[1,0,1]
	v_pk_fma_f32 v[102:103], v[46:47], v[108:109], v[102:103] op_sel_hi:[1,0,1]
	s_waitcnt lgkmcnt(2)
	v_mfma_f32_32x32x16_bf16 v[32:47], v[132:135], v[8:11], 0
	v_mfma_f32_32x32x16_bf16 v[32:47], v[128:131], v[12:15], v[32:47]
	ds_read_b128 v[8:11], v165 offset:64
	ds_read_b128 v[12:15], v165 offset:96
	v_pk_mul_f32 v[16:17], v[16:17], v[112:113] clamp
	v_pk_mul_f32 v[18:19], v[18:19], v[112:113] clamp
	v_pk_mul_f32 v[20:21], v[20:21], v[112:113] clamp
	v_pk_mul_f32 v[22:23], v[22:23], v[112:113] clamp
	v_pk_mul_f32 v[24:25], v[24:25], v[112:113] clamp
	v_pk_mul_f32 v[26:27], v[26:27], v[112:113] clamp
	v_pk_mul_f32 v[28:29], v[28:29], v[112:113] clamp
	v_pk_mul_f32 v[30:31], v[30:31], v[112:113] clamp
	v_pk_fma_f32 v[88:89], v[16:17], v[86:87], v[88:89] op_sel_hi:[1,0,1]
	v_pk_fma_f32 v[90:91], v[18:19], v[86:87], v[90:91] op_sel_hi:[1,0,1]
	v_pk_fma_f32 v[92:93], v[20:21], v[86:87], v[92:93] op_sel_hi:[1,0,1]
	v_pk_fma_f32 v[94:95], v[22:23], v[86:87], v[94:95] op_sel_hi:[1,0,1]
	v_pk_fma_f32 v[96:97], v[24:25], v[86:87], v[96:97] op_sel_hi:[1,0,1]
	v_pk_fma_f32 v[98:99], v[26:27], v[86:87], v[98:99] op_sel_hi:[1,0,1]
	v_pk_fma_f32 v[100:101], v[28:29], v[86:87], v[100:101] op_sel_hi:[1,0,1]
	v_pk_fma_f32 v[102:103], v[30:31], v[86:87], v[102:103] op_sel_hi:[1,0,1]
	v_pk_mul_f32 v[32:33], v[32:33], v[112:113] clamp
	v_pk_mul_f32 v[34:35], v[34:35], v[112:113] clamp
	v_pk_mul_f32 v[36:37], v[36:37], v[112:113] clamp
	v_pk_mul_f32 v[38:39], v[38:39], v[112:113] clamp
	v_pk_mul_f32 v[40:41], v[40:41], v[112:113] clamp
	v_pk_mul_f32 v[42:43], v[42:43], v[112:113] clamp
	v_pk_mul_f32 v[44:45], v[44:45], v[112:113] clamp
	v_pk_mul_f32 v[46:47], v[46:47], v[112:113] clamp
	v_pk_fma_f32 v[88:89], v[32:33], v[110:111], v[88:89] op_sel_hi:[1,0,1]
	v_pk_fma_f32 v[90:91], v[34:35], v[110:111], v[90:91] op_sel_hi:[1,0,1]
	v_pk_fma_f32 v[92:93], v[36:37], v[110:111], v[92:93] op_sel_hi:[1,0,1]
	v_pk_fma_f32 v[94:95], v[38:39], v[110:111], v[94:95] op_sel_hi:[1,0,1]
	v_pk_fma_f32 v[96:97], v[40:41], v[110:111], v[96:97] op_sel_hi:[1,0,1]
	v_pk_fma_f32 v[98:99], v[42:43], v[110:111], v[98:99] op_sel_hi:[1,0,1]
	v_pk_fma_f32 v[100:101], v[44:45], v[110:111], v[100:101] op_sel_hi:[1,0,1]
	v_pk_fma_f32 v[102:103], v[46:47], v[110:111], v[102:103] op_sel_hi:[1,0,1]
	s_waitcnt lgkmcnt(0)
	v_cmp_ge_f32_e64 s[40:41], v88, v122
	v_cmp_ge_f32_e64 s[42:43], v88, v123
	v_mov_b32_e32 v18, v124
	s_andn2_b64 s[42:43], s[42:43], s[40:41]
	s_mov_b64 exec, s[40:41]
	ds_add_rtn_u32 v16, v180, v222
	s_mov_b64 exec, s[42:43]
	ds_add_rtn_u32 v16, v171, v222
	s_mov_b64 exec, -1
	v_cmp_ge_f32_e64 s[44:45], v89, v122
	v_cmp_ge_f32_e64 s[22:23], v89, v123
	v_or_b32_e32 v19, 1, v124
	s_andn2_b64 s[22:23], s[22:23], s[44:45]
	s_mov_b64 exec, s[44:45]
	ds_add_rtn_u32 v17, v180, v222
	s_mov_b64 exec, s[22:23]
	ds_add_rtn_u32 v17, v171, v222
	s_mov_b64 exec, -1
	v_cmp_ge_f32_e64 s[20:21], v90, v122
	v_cmp_ge_f32_e64 s[2:3], v90, v123
	v_or_b32_e32 v24, 2, v124
	s_andn2_b64 s[2:3], s[2:3], s[20:21]
	s_mov_b64 exec, s[20:21]
	ds_add_rtn_u32 v23, v180, v222
	s_mov_b64 exec, s[2:3]
	ds_add_rtn_u32 v23, v171, v222
	s_mov_b64 exec, -1
	s_waitcnt lgkmcnt(4)
	v_and_b32_e32 v16, 0xff, v16
	s_mov_b64 exec, s[40:41]
	v_lshl_add_u32 v20, v16, 1, v179
	ds_write_b16 v20, v18
	s_mov_b64 exec, s[42:43]
	s_cbranch_execz .Lm6_nb0
; __device__ __forceinline__ unsigned sortable(float f) { const unsigned u = __float_as_uint(f); return u ^ ((unsigned)((int)u >> 31) | 0x80000000u); }
;     ...
;                 else if (sc[r] >= t_lo) { const unsigned key = (sortable(sc[r]) & 0xFFFFE000u) | (8191u - s);
;                     const unsigned pos = __hip_atomic_fetch_add(ccnt, 1u, __ATOMIC_RELAXED, __HIP_MEMORY_SCOPE_WORKGROUP); cand[pos & (DS_CAP - 1)] = key; }
	v_ashrrev_i32_e32 v22, 31, v88
	v_sub_u32_e32 v18, 0x1fff, v18
	v_lshl_add_u32 v20, v16, 2, v169
	v_bitop3_b32 v21, v22, v88, s64 bitop3:0x36
	v_and_or_b32 v21, v21, s65, v18
	ds_write_b32 v20, v21
